# phase-5 group-softmax reciprocal: IEEE 1/x sequence replaced by v_rcp_f32 (last in-loop division)
# baseline (speedup 1.0000x reference)
; DI unsigned pk2(float a, float b) { fl2_t f = {a, b}; bf2_t r = __builtin_convertvector(f, bf2_t); return __builtin_bit_cast(unsigned, r); }
; #define HSUM(v) do { v += __shfl_xor(v, 16, 64); v += __shfl_xor(v, 8, 64); v += __shfl_xor(v, 4, 64); v += __shfl_xor(v, 2, 64); v += __shfl_xor(v, 1, 64); } while (0)
; DI void phase5(const Params& p, char* lds0) {
;     ...
;       for (int j = 0; j < 8; ++j) {
;         float4 v = nx[j];
;         hv[j * 4 + 0] = v.x; hv[j * 4 + 1] = v.y; hv[j * 4 + 2] = v.z; hv[j * 4 + 3] = v.w;
;         ss += v.x * v.x + v.y * v.y + v.z * v.z + v.w * v.w;
;       }
;       if (i + 1 < 8) {
;         const float* x1 = p.out + (size_t)(t + 2) * D;
; #pragma unroll
;         for (int j = 0; j < 8; ++j) nx[j] = *(const float4*)(x1 + j * 128 + l32 * 4);
;       }
;     ...
;       HSUM(ss);
;       const float rstd = rsqrtf(ss * (1.f / 1024.f) + 1e-6f);
; #pragma unroll
;       for (int j = 0; j < 8; ++j) {
;         const int c = j * 128 + l32 * 4;
;         hv[j * 4 + 0] = hv[j * 4 + 0] * rstd * csv[j].x + shv[j].x;
;         hv[j * 4 + 1] = hv[j * 4 + 1] * rstd * csv[j].y + shv[j].y;
;         hv[j * 4 + 2] = hv[j * 4 + 2] * rstd * csv[j].z + shv[j].z;
;         hv[j * 4 + 3] = hv[j * 4 + 3] * rstd * csv[j].w + shv[j].w;
;         u32x2 o; o[0] = pk2(hv[j * 4 + 0], hv[j * 4 + 1]); o[1] = pk2(hv[j * 4 + 2], hv[j * 4 + 3]);
;         *(u32x2*)(H + (size_t)t * D + c) = o;
;       }
;       float lg[4];
; #pragma unroll
;       for (int n = 0; n < 4; ++n) {
;         float a = 0.f;
; #pragma unroll
;         for (int j = 0; j < 8; ++j) {
;           float4 wv = *(const float4*)(wg + n * 1024 + j * 128 + l32 * 4);
;           a += hv[j * 4 + 0] * wv.x + hv[j * 4 + 1] * wv.y + hv[j * 4 + 2] * wv.z + hv[j * 4 + 3] * wv.w;
.LBB0_259:
	s_waitcnt vmcnt(16)
	v_pk_mul_f32 v[160:161], v[94:95], v[94:95]
	s_waitcnt vmcnt(15)
	v_pk_mul_f32 v[164:165], v[90:91], v[90:91]
	v_pk_mul_f32 v[162:163], v[96:97], v[96:97]
	v_pk_mul_f32 v[166:167], v[92:93], v[92:93]
	v_add_f32_e32 v159, v161, v160
	v_add_f32_e32 v160, v165, v164
	v_add_f32_e32 v159, v162, v159
	v_add_f32_e32 v160, v166, v160
	s_waitcnt vmcnt(14)
	v_pk_mul_f32 v[168:169], v[86:87], v[86:87]
	v_add_f32_e32 v159, v163, v159
	v_add_f32_e32 v160, v167, v160
	v_pk_mul_f32 v[170:171], v[88:89], v[88:89]
	v_add_f32_e32 v159, v160, v159
	v_add_f32_e32 v160, v169, v168
	v_add_f32_e32 v160, v170, v160
	s_waitcnt vmcnt(13)
	v_pk_mul_f32 v[172:173], v[78:79], v[78:79]
	v_add_f32_e32 v160, v171, v160
	v_pk_mul_f32 v[188:189], v[80:81], v[80:81]
	v_add_f32_e32 v159, v160, v159
	v_add_f32_e32 v160, v173, v172
	v_add_f32_e32 v160, v188, v160
	s_waitcnt vmcnt(12)
	v_pk_mul_f32 v[190:191], v[70:71], v[70:71]
	v_add_f32_e32 v160, v189, v160
	v_pk_mul_f32 v[192:193], v[72:73], v[72:73]
	v_add_f32_e32 v159, v160, v159
	v_add_f32_e32 v160, v191, v190
	v_add_f32_e32 v160, v192, v160
	s_waitcnt vmcnt(11)
	v_pk_mul_f32 v[194:195], v[82:83], v[82:83]
	v_add_f32_e32 v160, v193, v160
	v_pk_mul_f32 v[196:197], v[84:85], v[84:85]
	v_add_f32_e32 v159, v160, v159
	v_add_f32_e32 v160, v194, v195
	v_add_f32_e32 v160, v160, v196
	s_waitcnt vmcnt(10)
	v_pk_mul_f32 v[198:199], v[74:75], v[74:75]
	v_add_f32_e32 v160, v160, v197
	v_pk_mul_f32 v[200:201], v[76:77], v[76:77]
	v_add_f32_e32 v159, v160, v159
	v_add_f32_e32 v160, v198, v199
	v_add_f32_e32 v160, v160, v200
	s_waitcnt vmcnt(9)
	v_pk_mul_f32 v[202:203], v[66:67], v[66:67]
	v_add_f32_e32 v160, v160, v201
	v_pk_mul_f32 v[204:205], v[68:69], v[68:69]
	v_add_f32_e32 v159, v159, v160
	v_add_f32_e32 v160, v202, v203
	v_add_f32_e32 v160, v160, v204
	v_add_f32_e32 v160, v160, v205
	v_add_f32_e32 v159, v159, v160
	ds_bpermute_b32 v160, v176, v159
	s_waitcnt lgkmcnt(0)
	v_add_f32_e32 v159, v159, v160
	ds_bpermute_b32 v160, v177, v159
	s_waitcnt lgkmcnt(0)
	v_add_f32_e32 v159, v159, v160
	ds_bpermute_b32 v160, v178, v159
	s_waitcnt lgkmcnt(0)
	v_add_f32_e32 v159, v159, v160
	ds_bpermute_b32 v160, v179, v159
	s_waitcnt lgkmcnt(0)
	v_add_f32_e32 v159, v159, v160
	ds_bpermute_b32 v160, v180, v159
	s_waitcnt lgkmcnt(0)
	v_add_f32_e32 v159, v159, v160
	v_fmamk_f32 v159, v159, 0x3a800000, v182
	v_mul_f32_e32 v160, 0x4b800000, v159
	v_cmp_gt_f32_e32 vcc, s40, v159
	s_nop 1
	v_cndmask_b32_e32 v159, v159, v160, vcc
	v_rsq_f32_e32 v159, v159
	s_nop 0
	v_mul_f32_e32 v160, 0x45800000, v159
	v_cndmask_b32_e32 v168, v159, v160, vcc
	v_pk_mul_f32 v[94:95], v[94:95], v[168:169] op_sel_hi:[1,0]
	v_ashrrev_i32_e32 v159, 31, v158
	v_pk_fma_f32 v[160:161], v[126:127], v[94:95], v[2:3]
	v_pk_mul_f32 v[94:95], v[96:97], v[168:169] op_sel_hi:[1,0]
	v_lshlrev_b64 v[164:165], 11, v[158:159]
	v_pk_fma_f32 v[162:163], v[128:129], v[94:95], v[4:5]
	v_pk_mul_f32 v[90:91], v[90:91], v[168:169] op_sel_hi:[1,0]
	v_cvt_pk_bf16_f32 v94, v160, v161
	v_cvt_pk_bf16_f32 v95, v162, v163
	v_lshl_add_u64 v[166:167], v[110:111], 0, v[164:165]
	v_pk_fma_f32 v[164:165], v[130:131], v[90:91], v[6:7]
	v_pk_mul_f32 v[90:91], v[92:93], v[168:169] op_sel_hi:[1,0]
	global_store_dwordx2 v[166:167], v[94:95], off
	v_pk_fma_f32 v[94:95], v[132:133], v[90:91], v[8:9]
	v_cvt_pk_bf16_f32 v90, v164, v165
	v_cvt_pk_bf16_f32 v91, v94, v95
	v_pk_mul_f32 v[86:87], v[86:87], v[168:169] op_sel_hi:[1,0]
	global_store_dwordx2 v[166:167], v[90:91], off offset:256
	v_pk_fma_f32 v[90:91], v[134:135], v[86:87], v[10:11]
	v_pk_mul_f32 v[86:87], v[88:89], v[168:169] op_sel_hi:[1,0]
	v_pk_mul_f32 v[78:79], v[78:79], v[168:169] op_sel_hi:[1,0]
	v_pk_fma_f32 v[92:93], v[136:137], v[86:87], v[12:13]
	v_pk_mul_f32 v[70:71], v[70:71], v[168:169] op_sel_hi:[1,0]
	v_cvt_pk_bf16_f32 v86, v90, v91
	v_cvt_pk_bf16_f32 v87, v92, v93
	v_pk_fma_f32 v[96:97], v[138:139], v[78:79], v[14:15]
	v_pk_mul_f32 v[78:79], v[80:81], v[168:169] op_sel_hi:[1,0]
	v_pk_fma_f32 v[80:81], v[142:143], v[70:71], v[18:19]
	v_pk_mul_f32 v[70:71], v[72:73], v[168:169] op_sel_hi:[1,0]
	global_store_dwordx2 v[166:167], v[86:87], off offset:512
	v_pk_fma_f32 v[86:87], v[144:145], v[70:71], v[20:21]
	v_cvt_pk_bf16_f32 v70, v80, v81
	v_cvt_pk_bf16_f32 v71, v86, v87
	v_pk_fma_f32 v[88:89], v[140:141], v[78:79], v[16:17]
	global_store_dwordx2 v[166:167], v[70:71], off offset:1024
	v_pk_mul_f32 v[70:71], v[82:83], v[168:169] op_sel_hi:[1,0]
	v_cvt_pk_bf16_f32 v78, v96, v97
	v_cvt_pk_bf16_f32 v79, v88, v89
	v_pk_fma_f32 v[82:83], v[146:147], v[70:71], v[22:23]
	v_pk_mul_f32 v[70:71], v[84:85], v[168:169] op_sel_hi:[1,0]
	global_store_dwordx2 v[166:167], v[78:79], off offset:768
	v_pk_fma_f32 v[78:79], v[148:149], v[70:71], v[24:25]
	v_cvt_pk_bf16_f32 v70, v82, v83
	v_cvt_pk_bf16_f32 v71, v78, v79
	global_store_dwordx2 v[166:167], v[70:71], off offset:1280
	v_pk_mul_f32 v[70:71], v[74:75], v[168:169] op_sel_hi:[1,0]
	v_pk_mul_f32 v[72:73], v[76:77], v[168:169] op_sel_hi:[1,0]
	v_pk_fma_f32 v[70:71], v[150:151], v[70:71], v[26:27]
	v_pk_fma_f32 v[72:73], v[152:153], v[72:73], v[28:29]
	v_cvt_pk_bf16_f32 v74, v70, v71
	v_cvt_pk_bf16_f32 v75, v72, v73
	global_store_dwordx2 v[166:167], v[74:75], off offset:1536
	ds_read_b128 v[74:77], v102 offset:9216
	ds_read_b128 v[188:191], v102 offset:9728
	v_mov_b32_e32 v204, v91
	v_mov_b32_e32 v205, v97
	v_pk_mul_f32 v[170:171], v[66:67], v[168:169] op_sel_hi:[1,0]
	v_pk_mul_f32 v[66:67], v[68:69], v[168:169] op_sel_hi:[1,0]
	s_waitcnt lgkmcnt(0)
; #define HSUM(v) do { v += __shfl_xor(v, 16, 64); v += __shfl_xor(v, 8, 64); v += __shfl_xor(v, 4, 64); v += __shfl_xor(v, 2, 64); v += __shfl_xor(v, 1, 64); } while (0)
; DI void phase5(const Params& p, char* lds0) {
;     ...
; #pragma unroll
;       for (int n = 0; n < 4; ++n) {
;         float a = 0.f;
; #pragma unroll
;         for (int j = 0; j < 8; ++j) {
;           float4 wv = *(const float4*)(wg + n * 1024 + j * 128 + l32 * 4);
;           a += hv[j * 4 + 0] * wv.x + hv[j * 4 + 1] * wv.y + hv[j * 4 + 2] * wv.z + hv[j * 4 + 3] * wv.w;
;         }
;         HSUM(a);
;         lg[n] = a + p.b_rg[n];
	v_mov_b32_e32 v85, v188
	v_mov_b32_e32 v188, v75
	v_mov_b32_e32 v84, v74
	v_mov_b32_e32 v68, v90
	v_mov_b32_e32 v69, v96
	v_pk_mul_f32 v[74:75], v[204:205], v[188:189]
	v_mov_b32_e32 v206, v92
	v_pk_fma_f32 v[74:75], v[68:69], v[84:85], v[74:75]
	v_mov_b32_e32 v84, v76
	v_mov_b32_e32 v85, v190
	v_mov_b32_e32 v207, v88
	v_pk_fma_f32 v[84:85], v[206:207], v[84:85], v[74:75]
	v_mov_b32_e32 v190, v77
	ds_read_b128 v[74:77], v102 offset:10240
	ds_read_b128 v[192:195], v102 offset:10752
	v_mov_b32_e32 v208, v93
	v_mov_b32_e32 v209, v89
	v_pk_fma_f32 v[168:169], v[208:209], v[190:191], v[84:85]
	v_mov_b32_e32 v212, v81
	s_waitcnt lgkmcnt(0)
	v_mov_b32_e32 v85, v192
	v_mov_b32_e32 v192, v75
	v_mov_b32_e32 v213, v83
	v_mov_b32_e32 v84, v74
	v_mov_b32_e32 v210, v80
	v_mov_b32_e32 v211, v82
	v_pk_mul_f32 v[74:75], v[212:213], v[192:193]
	v_mov_b32_e32 v188, v76
	v_pk_fma_f32 v[84:85], v[210:211], v[84:85], v[74:75]
	v_mov_b32_e32 v189, v194
	v_mov_b32_e32 v74, v86
	v_mov_b32_e32 v75, v78
	v_pk_fma_f32 v[84:85], v[74:75], v[188:189], v[84:85]
	ds_read_b128 v[188:191], v102 offset:8192
	ds_read_b128 v[196:199], v102 offset:12288
	v_mov_b32_e32 v194, v77
	v_mov_b32_e32 v76, v87
	v_mov_b32_e32 v77, v79
	v_pk_fma_f32 v[84:85], v[76:77], v[194:195], v[84:85]
	ds_read_b128 v[192:195], v102 offset:8704
	ds_read_b128 v[200:203], v102 offset:12800
	s_waitcnt lgkmcnt(2)
	v_pk_mov_b32 v[214:215], v[188:189], v[196:197] op_sel:[1,0]
	v_mov_b32_e32 v189, v197
	v_pk_mul_f32 v[188:189], v[188:189], v[160:161]
	v_mov_b32_e32 v196, v190
	v_pk_fma_f32 v[188:189], v[214:215], v[160:161], v[188:189] op_sel:[0,1,0] op_sel_hi:[1,0,1]
	v_mov_b32_e32 v197, v198
	v_pk_fma_f32 v[188:189], v[162:163], v[196:197], v[188:189] op_sel_hi:[0,1,1]
	v_mov_b32_e32 v198, v191
	v_pk_fma_f32 v[188:189], v[162:163], v[198:199], v[188:189] op_sel:[1,0,0]
	s_waitcnt vmcnt(7)
	v_pk_fma_f32 v[66:67], v[156:157], v[66:67], v[32:33]
	v_pk_add_f32 v[214:215], v[188:189], 0 op_sel_hi:[1,0]
	s_waitcnt lgkmcnt(0)
	v_pk_mov_b32 v[188:189], v[192:193], v[200:201] op_sel:[1,0]
	v_mov_b32_e32 v193, v201
	v_pk_mul_f32 v[190:191], v[164:165], v[192:193]
	v_cvt_pk_bf16_f32 v173, v66, v67
	v_pk_fma_f32 v[188:189], v[164:165], v[188:189], v[190:191] op_sel:[1,0,0] op_sel_hi:[0,1,1]
	v_mov_b32_e32 v190, v194
	v_mov_b32_e32 v191, v202
	v_pk_fma_f32 v[192:193], v[94:95], v[190:191], v[188:189] op_sel_hi:[0,1,1]
	ds_read_b128 v[188:191], v102 offset:13312
	ds_read_b128 v[196:199], v102 offset:13824
	v_mov_b32_e32 v202, v195
	v_pk_fma_f32 v[192:193], v[94:95], v[202:203], v[192:193] op_sel:[1,0,0]
	s_nop 0
	v_pk_add_f32 v[214:215], v[214:215], v[192:193]
	s_waitcnt lgkmcnt(0)
	v_mov_b32_e32 v193, v196
	v_mov_b32_e32 v196, v189
	v_mov_b32_e32 v192, v188
	v_pk_mul_f32 v[188:189], v[204:205], v[196:197]
	v_mov_b32_e32 v196, v190
	v_pk_fma_f32 v[188:189], v[68:69], v[192:193], v[188:189]
	ds_read_b128 v[192:195], v102 offset:14336
	ds_read_b128 v[200:203], v102 offset:14848
	v_mov_b32_e32 v197, v198
	v_pk_fma_f32 v[188:189], v[206:207], v[196:197], v[188:189]
	v_mov_b32_e32 v198, v191
	v_pk_fma_f32 v[216:217], v[208:209], v[198:199], v[188:189]
	s_waitcnt lgkmcnt(0)
	v_mov_b32_e32 v189, v200
	v_mov_b32_e32 v200, v193
	v_mov_b32_e32 v188, v192
	v_pk_mul_f32 v[190:191], v[212:213], v[200:201]
	v_mov_b32_e32 v196, v194
	v_pk_fma_f32 v[192:193], v[210:211], v[188:189], v[190:191]
	ds_read_b128 v[188:191], v102 offset:16384
	v_mov_b32_e32 v197, v202
	v_pk_fma_f32 v[192:193], v[74:75], v[196:197], v[192:193]
	v_mov_b32_e32 v202, v195
	v_pk_fma_f32 v[218:219], v[76:77], v[202:203], v[192:193]
	ds_read_b128 v[192:195], v102 offset:16896
	s_waitcnt lgkmcnt(1)
	v_mul_f32_e32 v172, v161, v189
	v_fmac_f32_e32 v172, v160, v188
	v_fmac_f32_e32 v172, v162, v190
	v_fmac_f32_e32 v172, v163, v191
	ds_read_b128 v[188:191], v102 offset:17408
	ds_read_b128 v[196:199], v102 offset:17920
	s_waitcnt lgkmcnt(2)
	v_mul_f32_e32 v193, v165, v193
	v_fmac_f32_e32 v193, v164, v192
	v_fmac_f32_e32 v193, v94, v194
	v_add_f32_e32 v172, 0, v172
	v_fmac_f32_e32 v193, v95, v195
	v_add_f32_e32 v172, v172, v193
	s_waitcnt lgkmcnt(0)
	v_mov_b32_e32 v193, v196
	v_mov_b32_e32 v196, v189
	v_mov_b32_e32 v192, v188
	v_pk_mul_f32 v[188:189], v[204:205], v[196:197]
	s_nop 0
	v_pk_fma_f32 v[188:189], v[68:69], v[192:193], v[188:189]
	v_mov_b32_e32 v192, v190
	v_mov_b32_e32 v193, v198
	v_pk_fma_f32 v[196:197], v[206:207], v[192:193], v[188:189]
	v_mov_b32_e32 v198, v191
	ds_read_b128 v[188:191], v102 offset:18432
	ds_read_b128 v[192:195], v102 offset:18944
	v_pk_fma_f32 v[196:197], v[208:209], v[198:199], v[196:197]
	s_nop 0
	v_add_f32_e32 v172, v172, v196
	v_add_f32_e32 v172, v172, v197
	s_waitcnt lgkmcnt(0)
	v_mov_b32_e32 v197, v192
	v_mov_b32_e32 v192, v189
	v_mov_b32_e32 v196, v188
	v_pk_mul_f32 v[188:189], v[212:213], v[192:193]
	v_mov_b32_e32 v192, v190
	v_pk_fma_f32 v[188:189], v[210:211], v[196:197], v[188:189]
	v_mov_b32_e32 v193, v194
	v_pk_fma_f32 v[192:193], v[74:75], v[192:193], v[188:189]
	v_mov_b32_e32 v194, v191
	ds_read_b128 v[188:191], v102 offset:20480
	v_pk_fma_f32 v[192:193], v[76:77], v[194:195], v[192:193]
	s_nop 0
	v_add_f32_e32 v172, v172, v192
	v_add_f32_e32 v220, v172, v193
	ds_read_b128 v[192:195], v102 offset:20992
	s_waitcnt lgkmcnt(1)
	v_mul_f32_e32 v172, v161, v189
	v_fmac_f32_e32 v172, v160, v188
	v_fmac_f32_e32 v172, v162, v190
	v_fmac_f32_e32 v172, v163, v191
	ds_read_b128 v[188:191], v102 offset:21504
	ds_read_b128 v[196:199], v102 offset:22016
	s_waitcnt lgkmcnt(2)
	v_mul_f32_e32 v193, v165, v193
	v_fmac_f32_e32 v193, v164, v192
	v_fmac_f32_e32 v193, v94, v194
	v_add_f32_e32 v172, 0, v172
	v_fmac_f32_e32 v193, v95, v195
	v_add_f32_e32 v172, v172, v193
	s_waitcnt lgkmcnt(0)
; #define HSUM(v) do { v += __shfl_xor(v, 16, 64); v += __shfl_xor(v, 8, 64); v += __shfl_xor(v, 4, 64); v += __shfl_xor(v, 2, 64); v += __shfl_xor(v, 1, 64); } while (0)
; DI void phase5(const Params& p, char* lds0) {
;     ...
;         *(u32x2*)(H + (size_t)t * D + c) = o;
;     ...
; #pragma unroll
;       for (int n = 0; n < 4; ++n) {
;         float a = 0.f;
; #pragma unroll
;         for (int j = 0; j < 8; ++j) {
;           float4 wv = *(const float4*)(wg + n * 1024 + j * 128 + l32 * 4);
;           a += hv[j * 4 + 0] * wv.x + hv[j * 4 + 1] * wv.y + hv[j * 4 + 2] * wv.z + hv[j * 4 + 3] * wv.w;
;         }
;         HSUM(a);
;         lg[n] = a + p.b_rg[n];
	v_mov_b32_e32 v193, v196
	v_mov_b32_e32 v196, v189
	v_mov_b32_e32 v192, v188
	v_pk_mul_f32 v[188:189], v[204:205], v[196:197]
	s_nop 0
	v_pk_fma_f32 v[68:69], v[68:69], v[192:193], v[188:189]
	v_mov_b32_e32 v188, v190
	v_mov_b32_e32 v189, v198
	v_pk_fma_f32 v[68:69], v[206:207], v[188:189], v[68:69]
	v_mov_b32_e32 v198, v191
	ds_read_b128 v[188:191], v102 offset:22528
	ds_read_b128 v[192:195], v102 offset:23040
	v_pk_fma_f32 v[68:69], v[208:209], v[198:199], v[68:69]
	ds_read_b128 v[196:199], v102 offset:11264
	ds_read_b128 v[200:203], v102 offset:11776
	v_add_f32_e32 v68, v172, v68
	v_add_f32_e32 v221, v68, v69
	s_waitcnt lgkmcnt(2)
	v_mov_b32_e32 v69, v192
	v_mov_b32_e32 v192, v189
	v_mov_b32_e32 v68, v188
	v_pk_mul_f32 v[188:189], v[212:213], v[192:193]
	s_waitcnt lgkmcnt(1)
	v_mov_b32_e32 v204, v198
	v_pk_fma_f32 v[188:189], v[210:211], v[68:69], v[188:189]
	v_pk_fma_f32 v[68:69], v[154:155], v[170:171], v[30:31]
	s_waitcnt lgkmcnt(0)
	v_mov_b32_e32 v205, v202
	v_cvt_pk_bf16_f32 v172, v68, v69
	global_store_dwordx2 v[166:167], v[172:173], off offset:1792
	v_mov_b32_e32 v166, v196
	v_mov_b32_e32 v167, v200
	v_mov_b32_e32 v200, v197
	v_mov_b32_e32 v202, v199
	ds_read_b128 v[170:173], v102 offset:15360
	ds_read_b128 v[196:199], v102 offset:15872
	v_mov_b32_e32 v212, v71
	v_mov_b32_e32 v213, v69
	v_mov_b32_e32 v210, v70
	v_mov_b32_e32 v211, v68
	v_pk_mul_f32 v[200:201], v[212:213], v[200:201]
	v_mov_b32_e32 v206, v72
	v_mov_b32_e32 v207, v66
	v_pk_fma_f32 v[166:167], v[210:211], v[166:167], v[200:201]
	v_mov_b32_e32 v208, v73
	v_mov_b32_e32 v209, v67
	v_pk_fma_f32 v[166:167], v[206:207], v[204:205], v[166:167]
	v_mov_b32_e32 v192, v190
	v_pk_fma_f32 v[200:201], v[208:209], v[202:203], v[166:167]
	s_waitcnt lgkmcnt(0)
	v_mov_b32_e32 v167, v196
	v_mov_b32_e32 v196, v171
	v_mov_b32_e32 v166, v170
	v_mov_b32_e32 v170, v172
	v_mov_b32_e32 v171, v198
	v_mov_b32_e32 v198, v173
	v_pk_mul_f32 v[172:173], v[212:213], v[196:197]
	v_mov_b32_e32 v196, v84
	v_pk_fma_f32 v[166:167], v[210:211], v[166:167], v[172:173]
	v_mov_b32_e32 v197, v218
	v_pk_fma_f32 v[166:167], v[206:207], v[170:171], v[166:167]
	v_mov_b32_e32 v218, v85
	v_pk_fma_f32 v[170:171], v[208:209], v[198:199], v[166:167]
	v_mov_b32_e32 v166, v168
	v_mov_b32_e32 v167, v216
	v_pk_add_f32 v[166:167], v[214:215], v[166:167]
	v_mov_b32_e32 v216, v169
	v_pk_add_f32 v[172:173], v[166:167], v[216:217]
	global_load_dwordx4 v[166:169], v101, s[28:29]
	v_pk_add_f32 v[172:173], v[172:173], v[196:197]
	v_mov_b32_e32 v193, v194
	v_pk_add_f32 v[84:85], v[172:173], v[218:219]
	v_mov_b32_e32 v172, v200
	v_mov_b32_e32 v173, v170
	v_pk_add_f32 v[84:85], v[84:85], v[172:173]
	v_mov_b32_e32 v170, v201
	v_pk_add_f32 v[84:85], v[84:85], v[170:171]
	ds_bpermute_b32 v170, v176, v84
	ds_bpermute_b32 v171, v176, v85
	v_pk_fma_f32 v[74:75], v[74:75], v[192:193], v[188:189]
	v_mov_b32_e32 v194, v191
	v_pk_fma_f32 v[74:75], v[76:77], v[194:195], v[74:75]
	s_waitcnt lgkmcnt(0)
	v_pk_add_f32 v[84:85], v[84:85], v[170:171]
	v_add_f32_e32 v74, v221, v74
	v_add_f32_e32 v192, v74, v75
	ds_read_b128 v[74:77], v102 offset:19456
	ds_read_b128 v[170:173], v102 offset:19968
	ds_bpermute_b32 v188, v177, v84
	ds_bpermute_b32 v189, v177, v85
	s_waitcnt lgkmcnt(3)
	v_mov_b32_e32 v190, v74
	s_waitcnt lgkmcnt(2)
	v_mov_b32_e32 v191, v170
	v_mov_b32_e32 v170, v75
	v_mov_b32_e32 v74, v76
	v_mov_b32_e32 v75, v172
	v_mov_b32_e32 v172, v77
	v_pk_mul_f32 v[76:77], v[212:213], v[170:171]
	s_waitcnt lgkmcnt(0)
	v_pk_add_f32 v[84:85], v[84:85], v[188:189]
	v_pk_fma_f32 v[76:77], v[210:211], v[190:191], v[76:77]
	ds_bpermute_b32 v188, v178, v84
	v_pk_fma_f32 v[74:75], v[206:207], v[74:75], v[76:77]
	ds_bpermute_b32 v189, v178, v85
	v_pk_fma_f32 v[190:191], v[208:209], v[172:173], v[74:75]
	ds_read_b128 v[74:77], v102 offset:23552
	ds_read_b128 v[170:173], v102 offset:24064
	v_add_f32_e32 v190, v220, v190
	v_add_f32_e32 v193, v190, v191
	ds_bpermute_b32 v194, v176, v193
	s_waitcnt lgkmcnt(2)
	v_mov_b32_e32 v190, v74
	s_waitcnt lgkmcnt(1)
	v_mov_b32_e32 v191, v170
	v_mov_b32_e32 v170, v75
	v_mov_b32_e32 v74, v76
	v_mov_b32_e32 v75, v172
	v_mov_b32_e32 v172, v77
	v_pk_mul_f32 v[76:77], v[212:213], v[170:171]
	s_nop 0
	v_pk_fma_f32 v[76:77], v[210:211], v[190:191], v[76:77]
	s_nop 0
	v_pk_fma_f32 v[74:75], v[206:207], v[74:75], v[76:77]
	s_nop 0
	v_pk_fma_f32 v[74:75], v[208:209], v[172:173], v[74:75]
	s_nop 0
	v_add_f32_e32 v74, v192, v74
	v_add_f32_e32 v76, v74, v75
	ds_bpermute_b32 v77, v176, v76
	v_pk_add_f32 v[74:75], v[84:85], v[188:189]
	s_waitcnt lgkmcnt(1)
	v_add_f32_e32 v84, v193, v194
	ds_bpermute_b32 v85, v177, v84
	s_waitcnt lgkmcnt(1)
	v_add_f32_e32 v170, v76, v77
	ds_bpermute_b32 v171, v177, v170
	ds_bpermute_b32 v76, v179, v74
	s_waitcnt lgkmcnt(2)
	v_add_f32_e32 v84, v84, v85
	ds_bpermute_b32 v85, v178, v84
	ds_bpermute_b32 v77, v179, v75
	s_waitcnt lgkmcnt(3)
	v_add_f32_e32 v170, v170, v171
	ds_bpermute_b32 v171, v178, v170
	s_waitcnt lgkmcnt(2)
	v_add_f32_e32 v84, v84, v85
	ds_bpermute_b32 v85, v179, v84
	s_waitcnt lgkmcnt(2)
	v_pk_add_f32 v[74:75], v[74:75], v[76:77]
	s_waitcnt lgkmcnt(1)
	v_add_f32_e32 v170, v170, v171
	ds_bpermute_b32 v171, v179, v170
	ds_bpermute_b32 v76, v180, v74
	ds_bpermute_b32 v77, v180, v75
	s_waitcnt lgkmcnt(3)
	v_add_f32_e32 v84, v84, v85
	ds_bpermute_b32 v85, v180, v84
	s_waitcnt lgkmcnt(3)
	v_add_f32_e32 v170, v170, v171
	ds_bpermute_b32 v171, v180, v170
	s_waitcnt lgkmcnt(2)
	v_pk_add_f32 v[74:75], v[74:75], v[76:77]
	s_waitcnt lgkmcnt(1)
	v_add_f32_e32 v76, v84, v85
	s_waitcnt vmcnt(0)
	v_pk_add_f32 v[74:75], v[166:167], v[74:75]
	v_add_f32_e32 v168, v168, v76
	s_waitcnt lgkmcnt(0)
; #define HSUM(v) do { v += __shfl_xor(v, 16, 64); v += __shfl_xor(v, 8, 64); v += __shfl_xor(v, 4, 64); v += __shfl_xor(v, 2, 64); v += __shfl_xor(v, 1, 64); } while (0)
; DI void phase5(const Params& p, char* lds0) {
;     ...
;       int g = 0; float gm = lg[0];
; #pragma unroll
;       for (int n = 1; n < 4; ++n) if (lg[n] > gm) { gm = lg[n]; g = n; }
;       float den = 0.f;
; #pragma unroll
;       for (int n = 0; n < 4; ++n) den += __expf(lg[n] - gm);
;       const float pgrp = 1.f / den;
;       float le[8];
; #pragma unroll
;       for (int e = 0; e < 8; ++e) {
;         const float* wr = wg + (4 + g * 8 + e) * 1024;
;         float a = 0.f;
; #pragma unroll
;         for (int j = 0; j < 8; ++j) {
;           float4 wv = *(const float4*)(wr + j * 128 + l32 * 4);
;           a += hv[j * 4 + 0] * wv.x + hv[j * 4 + 1] * wv.y + hv[j * 4 + 2] * wv.z + hv[j * 4 + 3] * wv.w;
;         }
;         HSUM(a);
;         le[e] = a + p.b_re[g * 8 + e];
;       }
	v_add_f32_e32 v76, v170, v171
	v_cmp_gt_f32_e32 vcc, v75, v74
	v_add_f32_e32 v167, v169, v76
	s_nop 0
	v_cndmask_b32_e32 v76, v74, v75, vcc
	v_cmp_gt_f32_e64 s[6:7], v168, v76
	s_nop 1
	v_cndmask_b32_e64 v169, v76, v168, s[6:7]
	v_cndmask_b32_e64 v76, 0, 8, vcc
	v_cndmask_b32_e64 v76, v76, 16, s[6:7]
	v_cmp_gt_f32_e32 vcc, v167, v169
	s_nop 1
	v_cndmask_b32_e64 v166, v76, 24, vcc
	v_lshl_or_b32 v170, v166, 12, v102
	ds_read_b128 v[188:191], v170 offset:26624
	ds_read_b128 v[192:195], v170 offset:27136
	ds_read_b128 v[196:199], v170 offset:24576
	ds_read_b128 v[200:203], v170 offset:28672
	ds_read_b128 v[204:207], v170 offset:27648
	ds_read_b128 v[208:211], v170 offset:28160
	ds_read_b128 v[212:215], v170 offset:25088
	ds_read_b128 v[216:219], v170 offset:29184
	s_waitcnt lgkmcnt(4)
	v_pk_mov_b32 v[76:77], v[196:197], v[200:201] op_sel:[1,0]
	v_mov_b32_e32 v197, v201
	v_pk_mul_f32 v[84:85], v[160:161], v[196:197]
	s_nop 0
	v_pk_fma_f32 v[76:77], v[160:161], v[76:77], v[84:85] op_sel:[1,0,0] op_sel_hi:[0,1,1]
	v_mov_b32_e32 v84, v198
	v_mov_b32_e32 v85, v202
	v_pk_fma_f32 v[76:77], v[162:163], v[84:85], v[76:77] op_sel_hi:[0,1,1]
	v_mov_b32_e32 v202, v199
	v_pk_fma_f32 v[76:77], v[162:163], v[202:203], v[76:77] op_sel:[1,0,0]
	s_waitcnt lgkmcnt(0)
	v_pk_mov_b32 v[84:85], v[212:213], v[216:217] op_sel:[1,0]
	v_mov_b32_e32 v213, v217
	ds_read_b128 v[196:199], v170 offset:26112
	ds_read_b128 v[200:203], v170 offset:25600
	ds_read_b128 v[220:223], v170 offset:29696
	v_pk_mul_f32 v[172:173], v[164:165], v[212:213]
	v_pk_add_f32 v[76:77], v[76:77], 0 op_sel_hi:[1,0]
	v_pk_fma_f32 v[84:85], v[164:165], v[84:85], v[172:173] op_sel:[1,0,0] op_sel_hi:[0,1,1]
	v_mov_b32_e32 v172, v214
	v_mov_b32_e32 v173, v218
	v_pk_fma_f32 v[84:85], v[94:95], v[172:173], v[84:85] op_sel_hi:[0,1,1]
	v_mov_b32_e32 v218, v215
	v_pk_fma_f32 v[84:85], v[94:95], v[218:219], v[84:85] op_sel:[1,0,0]
	ds_read_b128 v[212:215], v170 offset:30208
	v_pk_add_f32 v[76:77], v[76:77], v[84:85]
	s_waitcnt lgkmcnt(1)
	v_pk_mov_b32 v[84:85], v[200:201], v[220:221] op_sel:[1,0]
	v_mov_b32_e32 v201, v221
	v_pk_mul_f32 v[172:173], v[90:91], v[200:201]
	s_nop 0
	v_pk_fma_f32 v[84:85], v[90:91], v[84:85], v[172:173] op_sel:[1,0,0] op_sel_hi:[0,1,1]
	v_mov_b32_e32 v172, v202
	v_mov_b32_e32 v173, v222
	v_pk_fma_f32 v[84:85], v[92:93], v[172:173], v[84:85] op_sel_hi:[0,1,1]
	v_mov_b32_e32 v222, v203
	v_pk_fma_f32 v[84:85], v[92:93], v[222:223], v[84:85] op_sel:[1,0,0]
	ds_read_b128 v[200:203], v170 offset:30720
	v_pk_add_f32 v[76:77], v[76:77], v[84:85]
	s_waitcnt lgkmcnt(1)
	v_pk_mov_b32 v[84:85], v[196:197], v[212:213] op_sel:[1,0]
	v_mov_b32_e32 v197, v213
	v_pk_mul_f32 v[172:173], v[96:97], v[196:197]
	s_nop 0
	v_pk_fma_f32 v[84:85], v[96:97], v[84:85], v[172:173] op_sel:[1,0,0] op_sel_hi:[0,1,1]
	v_mov_b32_e32 v172, v198
	v_mov_b32_e32 v173, v214
	v_pk_fma_f32 v[84:85], v[88:89], v[172:173], v[84:85] op_sel_hi:[0,1,1]
	v_mov_b32_e32 v214, v199
	v_pk_fma_f32 v[84:85], v[88:89], v[214:215], v[84:85] op_sel:[1,0,0]
	ds_read_b128 v[196:199], v170 offset:31232
	v_pk_add_f32 v[76:77], v[76:77], v[84:85]
	s_waitcnt lgkmcnt(1)
	v_pk_mov_b32 v[84:85], v[188:189], v[200:201] op_sel:[1,0]
	v_mov_b32_e32 v189, v201
	v_pk_mul_f32 v[172:173], v[80:81], v[188:189]
	s_nop 0
	v_pk_fma_f32 v[84:85], v[80:81], v[84:85], v[172:173] op_sel:[1,0,0] op_sel_hi:[0,1,1]
	v_mov_b32_e32 v172, v190
	v_mov_b32_e32 v173, v202
	v_pk_fma_f32 v[84:85], v[86:87], v[172:173], v[84:85] op_sel_hi:[0,1,1]
	v_mov_b32_e32 v202, v191
	v_pk_fma_f32 v[84:85], v[86:87], v[202:203], v[84:85] op_sel:[1,0,0]
	ds_read_b128 v[188:191], v170 offset:31744
	v_pk_add_f32 v[76:77], v[76:77], v[84:85]
	v_mov_b32_e32 v84, v193
	s_waitcnt lgkmcnt(1)
	v_mov_b32_e32 v85, v196
	v_pk_mul_f32 v[84:85], v[82:83], v[84:85] op_sel:[1,0] op_sel_hi:[0,1]
	v_mov_b32_e32 v193, v197
	v_pk_fma_f32 v[84:85], v[82:83], v[192:193], v[84:85]
	v_mov_b32_e32 v172, v194
	v_mov_b32_e32 v173, v198
	v_pk_fma_f32 v[84:85], v[78:79], v[172:173], v[84:85] op_sel_hi:[0,1,1]
	v_mov_b32_e32 v198, v195
	v_pk_fma_f32 v[84:85], v[78:79], v[198:199], v[84:85] op_sel:[1,0,0]
	ds_read_b128 v[192:195], v170 offset:32256
	v_pk_add_f32 v[76:77], v[76:77], v[84:85]
	s_waitcnt lgkmcnt(1)
	v_mov_b32_e32 v84, v188
	v_mov_b32_e32 v85, v205
	v_pk_mul_f32 v[84:85], v[70:71], v[84:85]
	v_mov_b32_e32 v205, v189
	v_pk_fma_f32 v[84:85], v[70:71], v[204:205], v[84:85] op_sel:[0,0,1] op_sel_hi:[1,1,0]
	v_mov_b32_e32 v172, v206
	v_mov_b32_e32 v173, v190
	v_pk_fma_f32 v[84:85], v[72:73], v[172:173], v[84:85] op_sel_hi:[0,1,1]
	v_mov_b32_e32 v190, v207
	v_pk_fma_f32 v[84:85], v[72:73], v[190:191], v[84:85] op_sel:[1,0,0]
	ds_read_b128 v[188:191], v170 offset:32768
	v_pk_add_f32 v[76:77], v[76:77], v[84:85]
	s_waitcnt lgkmcnt(1)
	v_pk_mov_b32 v[84:85], v[208:209], v[192:193] op_sel:[1,0]
	v_mov_b32_e32 v209, v193
	v_pk_mul_f32 v[84:85], v[68:69], v[84:85] op_sel:[1,0] op_sel_hi:[0,1]
	v_pk_fma_f32 v[84:85], v[68:69], v[208:209], v[84:85]
	v_mov_b32_e32 v172, v210
	v_mov_b32_e32 v173, v194
	v_pk_fma_f32 v[84:85], v[66:67], v[172:173], v[84:85] op_sel_hi:[0,1,1]
	v_mov_b32_e32 v194, v211
	v_pk_fma_f32 v[84:85], v[66:67], v[194:195], v[84:85] op_sel:[1,0,0]
	ds_read_b128 v[192:195], v170 offset:33280
	s_waitcnt lgkmcnt(1)
	v_mul_f32_e32 v171, v161, v189
	v_fmac_f32_e32 v171, v160, v188
	v_fmac_f32_e32 v171, v162, v190
	v_fmac_f32_e32 v171, v163, v191
	ds_read_b128 v[188:191], v170 offset:33792
	s_waitcnt lgkmcnt(1)
	v_mul_f32_e32 v172, v165, v193
	v_fmac_f32_e32 v172, v164, v192
	v_fmac_f32_e32 v172, v94, v194
	v_add_f32_e32 v171, 0, v171
	v_fmac_f32_e32 v172, v95, v195
	ds_read_b128 v[192:195], v170 offset:34304
	v_add_f32_e32 v171, v171, v172
	s_waitcnt lgkmcnt(1)
; #define HSUM(v) do { v += __shfl_xor(v, 16, 64); v += __shfl_xor(v, 8, 64); v += __shfl_xor(v, 4, 64); v += __shfl_xor(v, 2, 64); v += __shfl_xor(v, 1, 64); } while (0)
; DI void phase5(const Params& p, char* lds0) {
;     ...
;       for (int e = 0; e < 8; ++e) {
;         const float* wr = wg + (4 + g * 8 + e) * 1024;
;         float a = 0.f;
; #pragma unroll
;         for (int j = 0; j < 8; ++j) {
;           float4 wv = *(const float4*)(wr + j * 128 + l32 * 4);
;           a += hv[j * 4 + 0] * wv.x + hv[j * 4 + 1] * wv.y + hv[j * 4 + 2] * wv.z + hv[j * 4 + 3] * wv.w;
;         }
;         HSUM(a);
;         le[e] = a + p.b_re[g * 8 + e];
;       }
	v_mul_f32_e32 v172, v91, v189
	v_fmac_f32_e32 v172, v90, v188
	v_fmac_f32_e32 v172, v92, v190
	v_fmac_f32_e32 v172, v93, v191
	ds_read_b128 v[188:191], v170 offset:34816
	v_add_f32_e32 v171, v171, v172
	s_waitcnt lgkmcnt(1)
	v_mul_f32_e32 v172, v97, v193
	v_fmac_f32_e32 v172, v96, v192
	v_fmac_f32_e32 v172, v88, v194
	v_fmac_f32_e32 v172, v89, v195
	ds_read_b128 v[192:195], v170 offset:35328
	v_pk_add_f32 v[76:77], v[76:77], v[84:85]
	v_add_f32_e32 v171, v171, v172
	s_waitcnt lgkmcnt(1)
	v_mul_f32_e32 v172, v81, v189
	ds_bpermute_b32 v84, v176, v76
	ds_bpermute_b32 v85, v176, v77
	v_fmac_f32_e32 v172, v80, v188
	v_fmac_f32_e32 v172, v86, v190
	v_fmac_f32_e32 v172, v87, v191
	ds_read_b128 v[188:191], v170 offset:35840
	v_add_f32_e32 v171, v171, v172
	s_waitcnt lgkmcnt(3)
	v_mul_f32_e32 v172, v83, v193
	v_fmac_f32_e32 v172, v82, v192
	s_waitcnt lgkmcnt(1)
	v_pk_add_f32 v[76:77], v[76:77], v[84:85]
	v_fmac_f32_e32 v172, v78, v194
	ds_bpermute_b32 v84, v177, v76
	ds_bpermute_b32 v85, v177, v77
	v_fmac_f32_e32 v172, v79, v195
	ds_read_b128 v[192:195], v170 offset:36352
	v_add_f32_e32 v171, v171, v172
	s_waitcnt lgkmcnt(3)
	v_mul_f32_e32 v172, v71, v189
	v_fmac_f32_e32 v172, v70, v188
	v_fmac_f32_e32 v172, v72, v190
	v_fmac_f32_e32 v172, v73, v191
	s_waitcnt lgkmcnt(1)
	v_pk_add_f32 v[76:77], v[76:77], v[84:85]
	v_add_f32_e32 v171, v171, v172
	s_waitcnt lgkmcnt(0)
	v_mul_f32_e32 v172, v69, v193
	ds_bpermute_b32 v84, v178, v76
	ds_bpermute_b32 v85, v178, v77
	v_fmac_f32_e32 v172, v68, v192
	v_fmac_f32_e32 v172, v66, v194
	v_fmac_f32_e32 v172, v67, v195
	v_add_f32_e32 v171, v171, v172
	ds_bpermute_b32 v172, v176, v171
	s_waitcnt lgkmcnt(1)
	v_pk_add_f32 v[76:77], v[76:77], v[84:85]
	ds_bpermute_b32 v84, v179, v76
	ds_bpermute_b32 v85, v179, v77
	ds_read_b128 v[188:191], v170 offset:36864
	s_waitcnt lgkmcnt(3)
	v_add_f32_e32 v171, v171, v172
	ds_bpermute_b32 v172, v177, v171
	ds_read_b128 v[192:195], v170 offset:37376
	s_waitcnt lgkmcnt(3)
	v_pk_add_f32 v[76:77], v[76:77], v[84:85]
	s_waitcnt lgkmcnt(2)
	v_mul_f32_e32 v84, v161, v189
	v_fmac_f32_e32 v84, v160, v188
	v_fmac_f32_e32 v84, v162, v190
	v_fmac_f32_e32 v84, v163, v191
	ds_read_b128 v[188:191], v170 offset:37888
	s_waitcnt lgkmcnt(2)
	v_add_f32_e32 v85, v171, v172
	s_waitcnt lgkmcnt(1)
	v_mul_f32_e32 v171, v165, v193
	v_fmac_f32_e32 v171, v164, v192
	v_fmac_f32_e32 v171, v94, v194
	v_add_f32_e32 v84, 0, v84
	v_fmac_f32_e32 v171, v95, v195
	ds_read_b128 v[192:195], v170 offset:38400
	v_add_f32_e32 v84, v84, v171
	s_waitcnt lgkmcnt(1)
	v_mul_f32_e32 v171, v91, v189
	v_fmac_f32_e32 v171, v90, v188
	v_fmac_f32_e32 v171, v92, v190
	v_fmac_f32_e32 v171, v93, v191
	ds_read_b128 v[188:191], v170 offset:38912
	v_add_f32_e32 v84, v84, v171
	s_waitcnt lgkmcnt(1)
	v_mul_f32_e32 v171, v97, v193
	v_fmac_f32_e32 v171, v96, v192
	v_fmac_f32_e32 v171, v88, v194
	v_fmac_f32_e32 v171, v89, v195
	ds_read_b128 v[192:195], v170 offset:39424
	v_add_f32_e32 v84, v84, v171
	s_waitcnt lgkmcnt(1)
	v_mul_f32_e32 v171, v81, v189
	v_fmac_f32_e32 v171, v80, v188
	v_fmac_f32_e32 v171, v86, v190
	v_fmac_f32_e32 v171, v87, v191
	ds_read_b128 v[188:191], v170 offset:39936
	v_add_f32_e32 v84, v84, v171
	s_waitcnt lgkmcnt(1)
	v_mul_f32_e32 v171, v83, v193
	v_fmac_f32_e32 v171, v82, v192
	v_fmac_f32_e32 v171, v78, v194
	v_fmac_f32_e32 v171, v79, v195
	ds_read_b128 v[192:195], v170 offset:40448
	v_add_f32_e32 v84, v84, v171
	s_waitcnt lgkmcnt(1)
	v_mul_f32_e32 v171, v71, v189
	v_fmac_f32_e32 v171, v70, v188
	v_fmac_f32_e32 v171, v72, v190
	v_fmac_f32_e32 v171, v73, v191
	ds_read_b128 v[188:191], v170 offset:40960
	v_add_f32_e32 v84, v84, v171
	s_waitcnt lgkmcnt(1)
	v_mul_f32_e32 v171, v69, v193
	v_fmac_f32_e32 v171, v68, v192
	v_fmac_f32_e32 v171, v66, v194
	v_fmac_f32_e32 v171, v67, v195
	ds_read_b128 v[192:195], v170 offset:41472
	s_waitcnt lgkmcnt(1)
	v_mul_f32_e32 v172, v161, v189
	v_fmac_f32_e32 v172, v160, v188
	v_fmac_f32_e32 v172, v162, v190
	v_fmac_f32_e32 v172, v163, v191
	ds_read_b128 v[188:191], v170 offset:41984
	s_waitcnt lgkmcnt(1)
	v_mul_f32_e32 v173, v165, v193
	v_fmac_f32_e32 v173, v164, v192
	v_fmac_f32_e32 v173, v94, v194
	v_add_f32_e32 v172, 0, v172
	v_fmac_f32_e32 v173, v95, v195
	ds_read_b128 v[192:195], v170 offset:42496
	v_add_f32_e32 v172, v172, v173
	s_waitcnt lgkmcnt(1)
	v_mul_f32_e32 v173, v91, v189
	v_fmac_f32_e32 v173, v90, v188
	v_fmac_f32_e32 v173, v92, v190
	v_fmac_f32_e32 v173, v93, v191
	ds_read_b128 v[188:191], v170 offset:43008
	v_add_f32_e32 v172, v172, v173
	s_waitcnt lgkmcnt(1)
	v_mul_f32_e32 v173, v97, v193
	v_fmac_f32_e32 v173, v96, v192
	v_fmac_f32_e32 v173, v88, v194
	v_fmac_f32_e32 v173, v89, v195
	ds_read_b128 v[192:195], v170 offset:43520
	v_add_f32_e32 v172, v172, v173
	s_waitcnt lgkmcnt(1)
	v_mul_f32_e32 v173, v81, v189
	v_fmac_f32_e32 v173, v80, v188
	v_fmac_f32_e32 v173, v86, v190
	v_fmac_f32_e32 v173, v87, v191
	ds_read_b128 v[188:191], v170 offset:44032
	v_add_f32_e32 v172, v172, v173
	s_waitcnt lgkmcnt(1)
	v_mul_f32_e32 v173, v83, v193
	v_fmac_f32_e32 v173, v82, v192
	v_fmac_f32_e32 v173, v78, v194
	v_fmac_f32_e32 v173, v79, v195
	ds_read_b128 v[192:195], v170 offset:44544
	v_add_f32_e32 v172, v172, v173
	s_waitcnt lgkmcnt(1)
	v_mul_f32_e32 v173, v71, v189
	v_fmac_f32_e32 v173, v70, v188
	v_fmac_f32_e32 v173, v72, v190
	v_fmac_f32_e32 v173, v73, v191
	v_add_f32_e32 v172, v172, v173
	s_waitcnt lgkmcnt(0)
	v_mul_f32_e32 v173, v69, v193
	v_fmac_f32_e32 v173, v68, v192
	v_fmac_f32_e32 v173, v66, v194
	v_fmac_f32_e32 v173, v67, v195
	v_add_f32_e32 v84, v84, v171
	v_add_f32_e32 v172, v172, v173
	ds_bpermute_b32 v171, v176, v84
	ds_bpermute_b32 v173, v176, v172
	ds_bpermute_b32 v188, v178, v85
	ds_read_b128 v[192:195], v170 offset:45056
	s_waitcnt lgkmcnt(3)
; #define HSUM(v) do { v += __shfl_xor(v, 16, 64); v += __shfl_xor(v, 8, 64); v += __shfl_xor(v, 4, 64); v += __shfl_xor(v, 2, 64); v += __shfl_xor(v, 1, 64); } while (0)
; DI void phase5(const Params& p, char* lds0) {
;     ...
;       for (int e = 0; e < 8; ++e) {
;         const float* wr = wg + (4 + g * 8 + e) * 1024;
;         float a = 0.f;
; #pragma unroll
;         for (int j = 0; j < 8; ++j) {
;           float4 wv = *(const float4*)(wr + j * 128 + l32 * 4);
;           a += hv[j * 4 + 0] * wv.x + hv[j * 4 + 1] * wv.y + hv[j * 4 + 2] * wv.z + hv[j * 4 + 3] * wv.w;
;         }
;         HSUM(a);
;         le[e] = a + p.b_re[g * 8 + e];
;       }
	v_add_f32_e32 v171, v84, v171
	s_waitcnt lgkmcnt(2)
	v_add_f32_e32 v172, v172, v173
	ds_bpermute_b32 v189, v177, v171
	ds_bpermute_b32 v173, v177, v172
	s_waitcnt lgkmcnt(3)
	v_add_f32_e32 v188, v85, v188
	ds_bpermute_b32 v190, v179, v188
	ds_bpermute_b32 v84, v180, v76
	s_waitcnt lgkmcnt(3)
	v_add_f32_e32 v171, v171, v189
	s_waitcnt lgkmcnt(2)
	v_add_f32_e32 v172, v172, v173
	ds_bpermute_b32 v189, v178, v171
	ds_bpermute_b32 v173, v178, v172
	ds_bpermute_b32 v85, v180, v77
	s_waitcnt lgkmcnt(2)
	v_add_f32_e32 v189, v171, v189
	v_add_f32_e32 v171, v188, v190
	s_waitcnt lgkmcnt(1)
	v_add_f32_e32 v190, v172, v173
	ds_bpermute_b32 v191, v179, v189
	ds_bpermute_b32 v196, v179, v190
	ds_bpermute_b32 v172, v180, v171
	s_waitcnt lgkmcnt(2)
	v_add_f32_e32 v173, v189, v191
	s_waitcnt lgkmcnt(1)
	v_add_f32_e32 v189, v190, v196
	ds_read_b128 v[196:199], v170 offset:45568
	v_mul_f32_e32 v191, v161, v193
	v_fmac_f32_e32 v191, v160, v192
	v_fmac_f32_e32 v191, v162, v194
	v_fmac_f32_e32 v191, v163, v195
	s_waitcnt lgkmcnt(0)
	v_mul_f32_e32 v197, v165, v197
	v_fmac_f32_e32 v197, v164, v196
	ds_read_b128 v[192:195], v170 offset:46080
	v_fmac_f32_e32 v197, v94, v198
	v_add_f32_e32 v191, 0, v191
	v_fmac_f32_e32 v197, v95, v199
	v_add_f32_e32 v191, v191, v197
	ds_read_b128 v[196:199], v170 offset:46592
	s_waitcnt lgkmcnt(1)
	v_mul_f32_e32 v193, v91, v193
	v_fmac_f32_e32 v193, v90, v192
	v_fmac_f32_e32 v193, v92, v194
	v_fmac_f32_e32 v193, v93, v195
	s_waitcnt lgkmcnt(0)
	v_mul_f32_e32 v197, v97, v197
	v_add_f32_e32 v191, v191, v193
	v_fmac_f32_e32 v197, v96, v196
	ds_read_b128 v[192:195], v170 offset:47104
	v_fmac_f32_e32 v197, v88, v198
	v_fmac_f32_e32 v197, v89, v199
	v_add_f32_e32 v191, v191, v197
	ds_read_b128 v[196:199], v170 offset:47616
	s_waitcnt lgkmcnt(1)
	v_mul_f32_e32 v193, v81, v193
	v_fmac_f32_e32 v193, v80, v192
	v_fmac_f32_e32 v193, v86, v194
	v_fmac_f32_e32 v193, v87, v195
	s_waitcnt lgkmcnt(0)
	v_mul_f32_e32 v197, v83, v197
	v_add_f32_e32 v191, v191, v193
	v_fmac_f32_e32 v197, v82, v196
	ds_read_b128 v[192:195], v170 offset:48128
	v_fmac_f32_e32 v197, v78, v198
	v_fmac_f32_e32 v197, v79, v199
	v_add_f32_e32 v191, v191, v197
	ds_read_b128 v[196:199], v170 offset:48640
	s_waitcnt lgkmcnt(1)
	v_mul_f32_e32 v193, v71, v193
	v_fmac_f32_e32 v193, v70, v192
	v_fmac_f32_e32 v193, v72, v194
	v_fmac_f32_e32 v193, v73, v195
	s_waitcnt lgkmcnt(0)
	v_mul_f32_e32 v197, v69, v197
	v_add_f32_e32 v191, v191, v193
	v_fmac_f32_e32 v197, v68, v196
	ds_read_b128 v[192:195], v170 offset:49152
	v_fmac_f32_e32 v197, v66, v198
	v_fmac_f32_e32 v197, v67, v199
	v_add_f32_e32 v191, v191, v197
	ds_read_b128 v[196:199], v170 offset:49664
	s_waitcnt lgkmcnt(1)
	v_mul_f32_e32 v193, v161, v193
	v_fmac_f32_e32 v193, v160, v192
	v_fmac_f32_e32 v193, v162, v194
	v_fmac_f32_e32 v193, v163, v195
	s_waitcnt lgkmcnt(0)
	v_mul_f32_e32 v197, v165, v197
	v_add_f32_e32 v201, 0, v193
	v_fmac_f32_e32 v197, v164, v196
	ds_read_b128 v[192:195], v170 offset:50176
	v_fmac_f32_e32 v197, v94, v198
	v_fmac_f32_e32 v197, v95, v199
	v_add_f32_e32 v201, v201, v197
	ds_read_b128 v[196:199], v170 offset:50688
	s_waitcnt lgkmcnt(1)
	v_mul_f32_e32 v193, v91, v193
	v_fmac_f32_e32 v193, v90, v192
	v_fmac_f32_e32 v193, v92, v194
	v_fmac_f32_e32 v193, v93, v195
	s_waitcnt lgkmcnt(0)
	v_mul_f32_e32 v197, v97, v197
	v_add_f32_e32 v201, v201, v193
	v_fmac_f32_e32 v197, v96, v196
	ds_read_b128 v[192:195], v170 offset:51200
	v_fmac_f32_e32 v197, v88, v198
	v_fmac_f32_e32 v197, v89, v199
	v_add_f32_e32 v201, v201, v197
	ds_read_b128 v[196:199], v170 offset:51712
	s_waitcnt lgkmcnt(1)
	v_mul_f32_e32 v193, v81, v193
	v_fmac_f32_e32 v193, v80, v192
	v_fmac_f32_e32 v193, v86, v194
	v_fmac_f32_e32 v193, v87, v195
	s_waitcnt lgkmcnt(0)
	v_mul_f32_e32 v197, v83, v197
	v_add_f32_e32 v201, v201, v193
	v_fmac_f32_e32 v197, v82, v196
	ds_read_b128 v[192:195], v170 offset:52224
	v_fmac_f32_e32 v197, v78, v198
	v_fmac_f32_e32 v197, v79, v199
	v_add_f32_e32 v201, v201, v197
	ds_read_b128 v[196:199], v170 offset:52736
	s_waitcnt lgkmcnt(1)
	v_mul_f32_e32 v193, v71, v193
	v_fmac_f32_e32 v193, v70, v192
	v_fmac_f32_e32 v193, v72, v194
	v_fmac_f32_e32 v193, v73, v195
	s_waitcnt lgkmcnt(0)
	v_mul_f32_e32 v197, v69, v197
	v_add_f32_e32 v201, v201, v193
	v_fmac_f32_e32 v197, v68, v196
	ds_read_b128 v[192:195], v170 offset:53248
	v_fmac_f32_e32 v197, v66, v198
	v_fmac_f32_e32 v197, v67, v199
	v_add_f32_e32 v201, v201, v197
	ds_read_b128 v[196:199], v170 offset:53760
	s_waitcnt lgkmcnt(1)
	v_mul_f32_e32 v161, v161, v193
	v_fmac_f32_e32 v161, v160, v192
	v_fmac_f32_e32 v161, v162, v194
	v_fmac_f32_e32 v161, v163, v195
	s_waitcnt lgkmcnt(0)
	v_mul_f32_e32 v165, v165, v197
	v_add_f32_e32 v192, 0, v161
	v_fmac_f32_e32 v165, v164, v196
	ds_read_b128 v[160:163], v170 offset:54272
	v_fmac_f32_e32 v165, v94, v198
	v_fmac_f32_e32 v165, v95, v199
	v_add_f32_e32 v94, v192, v165
	ds_read_b128 v[192:195], v170 offset:54784
	s_waitcnt lgkmcnt(1)
	v_mul_f32_e32 v91, v91, v161
	v_fmac_f32_e32 v91, v90, v160
	v_fmac_f32_e32 v91, v92, v162
	v_fmac_f32_e32 v91, v93, v163
	s_waitcnt lgkmcnt(0)
	v_mul_f32_e32 v95, v97, v193
	v_add_f32_e32 v94, v94, v91
	v_fmac_f32_e32 v95, v96, v192
	ds_read_b128 v[90:93], v170 offset:55296
	v_fmac_f32_e32 v95, v88, v194
	v_fmac_f32_e32 v95, v89, v195
	v_add_f32_e32 v88, v94, v95
	ds_read_b128 v[94:97], v170 offset:55808
	s_waitcnt lgkmcnt(1)
	v_mul_f32_e32 v81, v81, v91
	v_fmac_f32_e32 v81, v80, v90
	v_fmac_f32_e32 v81, v86, v92
	v_fmac_f32_e32 v81, v87, v93
	s_waitcnt lgkmcnt(0)
; #define HSUM(v) do { v += __shfl_xor(v, 16, 64); v += __shfl_xor(v, 8, 64); v += __shfl_xor(v, 4, 64); v += __shfl_xor(v, 2, 64); v += __shfl_xor(v, 1, 64); } while (0)
; DI void phase5(const Params& p, char* lds0) {
;     ...
;         HSUM(a);
;         le[e] = a + p.b_re[g * 8 + e];
;       }
;     ...
;       int i1 = 0; float v1 = le[0];
; #pragma unroll
;       for (int e = 1; e < 8; ++e) if (le[e] > v1) { v1 = le[e]; i1 = e; }
;       int i2 = -1; float v2 = -3.0e38f;
; #pragma unroll
;       for (int e = 0; e < 8; ++e) if (e != i1 && le[e] > v2) { v2 = le[e]; i2 = e; }
;       const float e2 = __expf(v2 - v1);
;       const float w1 = pgrp / (1.f + e2), w2 = pgrp * e2 / (1.f + e2);
;       if (l32 == 0) {
;         const int li0 = (g * 8 + i1) * 2, li1 = (g * 8 + i2) * 2 + 1;
;         const int lp0 = atomicAdd(&hist[li0], 1), lp1 = atomicAdd(&hist[li1], 1);
;         info[tl * 4 + 0] = li0; info[tl * 4 + 1] = li1; info[tl * 4 + 2] = lp0; info[tl * 4 + 3] = lp1;
;         gate[t] = w1; gate[T + t] = w2;
	v_mul_f32_e32 v87, v83, v95
	v_fmac_f32_e32 v87, v82, v94
	v_fmac_f32_e32 v87, v78, v96
	v_add_f32_e32 v86, v88, v81
	ds_read_b128 v[80:83], v170 offset:56320
	v_fmac_f32_e32 v87, v79, v97
	v_add_f32_e32 v78, v86, v87
	ds_read_b128 v[86:89], v170 offset:56832
	ds_bpermute_b32 v200, v176, v191
	s_waitcnt lgkmcnt(2)
	v_mul_f32_e32 v71, v71, v81
	v_fmac_f32_e32 v71, v70, v80
	v_fmac_f32_e32 v71, v72, v82
	s_waitcnt lgkmcnt(1)
	v_mul_f32_e32 v69, v69, v87
	v_fmac_f32_e32 v69, v68, v86
	v_fmac_f32_e32 v71, v73, v83
	v_fmac_f32_e32 v69, v66, v88
	v_add_f32_e32 v70, v78, v71
	v_fmac_f32_e32 v69, v67, v89
	v_add_f32_e32 v66, v70, v69
	ds_bpermute_b32 v202, v176, v201
	ds_bpermute_b32 v67, v176, v66
	s_waitcnt lgkmcnt(2)
	v_add_f32_e32 v68, v191, v200
	ds_bpermute_b32 v69, v177, v68
	ds_bpermute_b32 v188, v180, v173
	s_waitcnt lgkmcnt(3)
	v_add_f32_e32 v70, v201, v202
	s_waitcnt lgkmcnt(2)
	v_add_f32_e32 v66, v66, v67
	ds_bpermute_b32 v71, v177, v70
	ds_bpermute_b32 v67, v177, v66
	s_waitcnt lgkmcnt(3)
	v_add_f32_e32 v68, v68, v69
	ds_bpermute_b32 v69, v178, v68
	ds_bpermute_b32 v190, v180, v189
	s_waitcnt lgkmcnt(3)
	v_add_f32_e32 v70, v70, v71
	s_waitcnt lgkmcnt(2)
	v_add_f32_e32 v66, v66, v67
	ds_bpermute_b32 v71, v178, v70
	ds_bpermute_b32 v67, v178, v66
	s_waitcnt lgkmcnt(3)
	v_add_f32_e32 v68, v68, v69
	ds_bpermute_b32 v69, v179, v68
	s_waitcnt lgkmcnt(2)
	v_add_f32_e32 v70, v70, v71
	s_waitcnt lgkmcnt(1)
	v_add_f32_e32 v72, v66, v67
	ds_bpermute_b32 v71, v179, v70
	ds_bpermute_b32 v73, v179, v72
	s_waitcnt lgkmcnt(2)
	v_add_f32_e32 v66, v68, v69
	ds_bpermute_b32 v67, v180, v66
	s_waitcnt lgkmcnt(2)
	v_add_f32_e32 v68, v70, v71
	s_waitcnt lgkmcnt(1)
	v_add_f32_e32 v70, v72, v73
	ds_bpermute_b32 v69, v180, v68
	ds_bpermute_b32 v71, v180, v70
	s_and_saveexec_b64 s[38:39], s[4:5]
	s_cbranch_execz .LBB0_255
	v_lshlrev_b32_e32 v72, 2, v166
	global_load_dwordx4 v[78:81], v72, s[30:31] offset:16
	global_load_dwordx4 v[86:89], v72, s[30:31]
	s_waitcnt lgkmcnt(1)
	v_add_f32_e32 v68, v68, v69
	v_add_f32_e32 v69, v66, v67
	v_cndmask_b32_e32 v66, v169, v167, vcc
	v_sub_f32_e32 v67, v74, v66
	v_sub_f32_e32 v74, v75, v66
	v_mul_f32_e32 v67, 0x3fb8aa3b, v67
	v_sub_f32_e32 v75, v168, v66
	v_mul_f32_e32 v74, 0x3fb8aa3b, v74
	v_exp_f32_e32 v67, v67
	v_sub_f32_e32 v66, v167, v66
	v_mul_f32_e32 v75, 0x3fb8aa3b, v75
	v_exp_f32_e32 v74, v74
	v_mul_f32_e32 v66, 0x3fb8aa3b, v66
	v_exp_f32_e32 v75, v75
	v_exp_f32_e32 v66, v66
	v_add_f32_e32 v67, 0, v67
	v_add_f32_e32 v67, v74, v67
	v_add_f32_e32 v67, v75, v67
	v_add_f32_e32 v74, v66, v67
	v_pk_add_f32 v[66:67], v[76:77], v[84:85]
	v_add_f32_e32 v73, v171, v172
	v_rcp_f32_e32 v74, v74
	v_add_f32_e32 v72, v173, v188
	s_waitcnt lgkmcnt(0)
	v_add_f32_e32 v70, v70, v71
	v_add_f32_e32 v71, v189, v190
	s_waitcnt vmcnt(1)
	v_add_f32_e32 v71, v71, v78
	s_waitcnt vmcnt(0)
	v_pk_add_f32 v[66:67], v[66:67], v[86:87]
	v_add_f32_e32 v73, v73, v88
	v_cmp_gt_f32_e32 vcc, v67, v66
	v_add_f32_e32 v72, v72, v89
	v_add_f32_e32 v69, v69, v79
	v_cndmask_b32_e32 v75, v66, v67, vcc
	v_cmp_gt_f32_e64 s[8:9], v73, v75
	v_cndmask_b32_e64 v76, 0, 1, vcc
	v_add_f32_e32 v68, v68, v80
	v_cndmask_b32_e64 v75, v75, v73, s[8:9]
	v_cmp_gt_f32_e32 vcc, v72, v75
	v_cndmask_b32_e64 v76, v76, 2, s[8:9]
	v_add_f32_e32 v70, v70, v81
	v_cndmask_b32_e32 v75, v75, v72, vcc
	v_cmp_gt_f32_e64 s[8:9], v71, v75
	v_cndmask_b32_e64 v76, v76, 3, vcc
	v_cmp_nlt_f32_e64 s[6:7], s41, v66
	v_cndmask_b32_e64 v75, v75, v71, s[8:9]
	v_cmp_gt_f32_e32 vcc, v69, v75
	v_cndmask_b32_e64 v76, v76, 4, s[8:9]
	s_nop 0
	v_cndmask_b32_e32 v75, v75, v69, vcc
	v_cmp_gt_f32_e64 s[8:9], v68, v75
	v_cndmask_b32_e64 v76, v76, 5, vcc
	s_nop 0
	v_cndmask_b32_e64 v75, v75, v68, s[8:9]
	v_cndmask_b32_e64 v76, v76, 6, s[8:9]
	v_cmp_ngt_f32_e32 vcc, v70, v75
	s_and_b64 s[46:47], s[8:9], vcc
	s_nop 0
	v_cndmask_b32_e32 v76, 7, v76, vcc
	v_cmp_eq_u32_e64 s[18:19], 0, v76
	s_or_b64 s[6:7], s[18:19], s[6:7]
	v_cndmask_b32_e64 v66, v66, v185, s[6:7]
	v_cmp_ne_u32_e64 s[16:17], 1, v76
	v_cmp_gt_f32_e64 s[18:19], v67, v66
	v_cndmask_b32_e64 v77, 0, -1, s[6:7]
	s_and_b64 s[6:7], s[16:17], s[18:19]
	v_cndmask_b32_e64 v66, v66, v67, s[6:7]
	v_cmp_ne_u32_e64 s[14:15], 2, v76
	v_cmp_gt_f32_e64 s[16:17], v73, v66
	v_cndmask_b32_e64 v67, v77, 1, s[6:7]
	s_and_b64 s[6:7], s[14:15], s[16:17]
	v_cndmask_b32_e64 v66, v66, v73, s[6:7]
	v_cmp_ne_u32_e64 s[12:13], 3, v76
	v_cmp_gt_f32_e64 s[14:15], v72, v66
	v_cndmask_b32_e64 v67, v67, 2, s[6:7]
	s_and_b64 s[6:7], s[12:13], s[14:15]
	v_cndmask_b32_e64 v66, v66, v72, s[6:7]
	v_cmp_ne_u32_e64 s[10:11], 4, v76
	v_cmp_gt_f32_e64 s[12:13], v71, v66
	v_cndmask_b32_e64 v67, v67, 3, s[6:7]
	s_and_b64 s[6:7], s[10:11], s[12:13]
	v_cndmask_b32_e64 v66, v66, v71, s[6:7]
	v_cmp_ne_u32_e64 s[8:9], 5, v76
	v_cmp_gt_f32_e64 s[10:11], v69, v66
	s_and_b64 s[8:9], s[8:9], s[10:11]
	v_cndmask_b32_e64 v66, v66, v69, s[8:9]
	v_cmp_ngt_f32_e64 s[10:11], v68, v66
	s_or_b64 s[10:11], s[46:47], s[10:11]
	v_cndmask_b32_e32 v75, v70, v75, vcc
	v_cndmask_b32_e64 v66, v68, v66, s[10:11]
	v_cmp_gt_f32_e64 s[12:13], v70, v66
	s_and_b64 vcc, vcc, s[12:13]
	v_cndmask_b32_e32 v66, v66, v70, vcc
	v_sub_f32_e32 v66, v66, v75
	v_mul_f32_e32 v66, 0x3fb8aa3b, v66
	v_exp_f32_e32 v66, v66
	v_cndmask_b32_e64 v67, v67, 4, s[6:7]
	v_cndmask_b32_e64 v67, v67, 5, s[8:9]
	v_cndmask_b32_e64 v67, 6, v67, s[10:11]
	v_mul_f32_e32 v68, v74, v66
	v_add_f32_e32 v66, 1.0, v66
	v_cndmask_b32_e64 v67, v67, 7, vcc
	v_rcp_f32_e32 v69, v66
	v_or_b32_e32 v75, v76, v166
	v_mul_f32_e32 v70, v68, v69
	v_add_u32_e32 v67, v67, v166
	v_lshl_add_u32 v68, v75, 3, v1
	ds_add_rtn_u32 v68, v68, v183
	v_lshl_add_u32 v69, v67, 3, v1
	ds_add_rtn_u32 v69, v69, v183 offset:4
	v_rcp_f32_e32 v71, v66
	s_nop 0
	v_mul_f32_e32 v71, v74, v71
	v_lshlrev_b32_e32 v66, 1, v75
	v_lshl_or_b32 v67, v67, 1, 1
	s_waitcnt lgkmcnt(0)
	ds_write_b128 v187, v[66:69]
	v_lshl_add_u64 v[66:67], v[158:159], 2, s[22:23]
	global_store_dword v[66:67], v71, off
	v_add_co_u32_e32 v66, vcc, 0x60000, v66
	s_nop 1
	v_addc_co_u32_e32 v67, vcc, 0, v67, vcc
	global_store_dword v[66:67], v70, off
	s_branch .LBB0_255
